# attention work mapping: the 4 workgroups of an XCD group walk the same (b,h) together, each taking q-blocks j and 7-j (equal 36 key tiles), so K/V tile reads are shared through L2
# speedup vs baseline: 1.0844x; 1.0006x over previous
.LBB0_40:
	s_or_b64 exec, exec, s[8:9]
	v_max_f32_e32 v2, v2, v2
	v_max_f32_e32 v1, v1, v1
	v_max_f32_e32 v1, v1, v2
	v_max_f32_e32 v2, v4, v4
	v_max_f32_e32 v3, v3, v3
	v_max_f32_e32 v2, v3, v2
	v_mul_f32_e32 v1, 0x41622ae0, v1
	v_mul_f32_e32 v1, v1, v2
	v_min_f32_e32 v165, 0x42700000, v1
	s_cmpk_gt_i32 s14, 0xff
	s_waitcnt lgkmcnt(0)
	s_barrier
	s_cbranch_scc1 .LBB0_75
	s_add_u32 s7, s36, 0x17600000
	v_lshlrev_b32_e32 v2, 1, v164
	v_lshrrev_b32_e32 v3, 1, v164
	v_lshlrev_b32_e32 v5, 4, v164
	s_addc_u32 s25, s37, 0
	v_and_b32_e32 v1, 19, v164
	v_and_b32_e32 v2, 8, v2
	v_and_b32_e32 v3, 4, v3
	v_and_b32_e32 v134, 0x70, v5
	v_mov_b32_e32 v135, v0
	s_add_u32 s8, s36, 0x900000
	v_or3_b32 v1, v1, v2, v3
	v_lshl_add_u64 v[2:3], s[36:37], 0, v[134:135]
	s_mov_b64 s[38:39], 0x3600000
	s_addc_u32 s9, s37, 0
	v_lshl_add_u64 v[136:137], v[2:3], 0, s[38:39]
	s_mov_b64 s[38:39], 0xf600000
	s_add_u32 s22, s36, 0x800000
	v_ashrrev_i32_e32 v132, 3, v164
	s_movk_i32 s31, 0xff
	v_lshl_add_u64 v[138:139], v[2:3], 0, s[38:39]
	s_mov_b64 s[38:39], 0x13600000
	v_and_b32_e32 v142, 48, v5
	v_mov_b32_e32 v143, v0
	s_addc_u32 s23, s37, 0
	v_ashrrev_i32_e32 v133, 31, v132
	v_cmp_lt_i32_e64 s[42:43], s31, v164
	v_lshl_add_u64 v[140:141], v[2:3], 0, s[38:39]
	s_movk_i32 s31, 0x140
	v_lshl_add_u64 v[2:3], s[36:37], 0, v[142:143]
	s_mov_b64 s[38:39], 0x600000
	s_mov_b32 s46, s34
	s_cmp_eq_u32 s30, 0x100
	s_cbranch_scc0 .Latt_map_done
	s_and_b32 s46, s34, 0xe7
.Latt_map_done:
	s_ashr_i32 s47, s46, 31
	v_cmp_gt_u32_e64 s[44:45], s31, v164
	v_lshl_add_u64 v[144:145], v[2:3], 0, s[38:39]
	s_movk_i32 s31, 0xd0
	s_lshl_b64 s[38:39], s[46:47], 18
	v_lshlrev_b64 v[10:11], 7, v[132:133]
	v_ashrrev_i32_e32 v135, 2, v164
	v_mul_lo_u32 v143, v132, s31
	v_lshl_add_u64 v[12:13], s[38:39], 0, v[10:11]
	v_add_u32_e32 v186, 0, v143
	v_mul_lo_u32 v188, v135, s31
	v_lshlrev_b32_e32 v2, 6, v132
	s_lshl_b32 s31, s20, 12
	v_lshrrev_b32_e32 v8, 3, v227
	v_or_b32_e32 v12, v12, v134
	v_and_b32_e32 v184, 31, v164
	v_lshrrev_b32_e32 v185, 5, v227
	v_sub_u32_e32 v7, v186, v2
	s_add_i32 s31, s31, 0
	v_lshlrev_b32_e32 v15, 7, v8
	v_lshlrev_b32_e32 v2, 10, v8
	v_or_b32_e32 v4, 8, v8
	v_or_b32_e32 v6, 16, v8
	v_or_b32_e32 v8, 24, v8
	v_lshl_add_u64 v[12:13], s[36:37], 0, v[12:13]
	s_mov_b64 s[38:39], 0x3602000
	v_or_b32_e32 v10, v10, v134
	v_add_u32_e32 v3, 0, v188
	v_mul_u32_u24_e32 v190, 0xd0, v1
	v_lshl_add_u32 v1, v184, 7, s31
	v_lshlrev_b32_e32 v9, 3, v185
	v_add_u32_e32 v14, s31, v134
	v_lshlrev_b32_e32 v16, 7, v4
	v_lshlrev_b32_e32 v4, 10, v4
	v_lshlrev_b32_e32 v17, 7, v6
	v_lshlrev_b32_e32 v6, 10, v6
	v_lshlrev_b32_e32 v18, 7, v8
	v_lshlrev_b32_e32 v8, 10, v8
	v_lshl_add_u64 v[146:147], v[12:13], 0, s[38:39]
	s_ashr_i32 s31, s30, 31
	v_lshl_add_u64 v[10:11], s[36:37], 0, v[10:11]
	s_mov_b64 s[38:39], 0xf620000
	s_ashr_i32 s26, s24, 7
	s_lshl_b32 s27, s20, 5
	v_lshlrev_b32_e32 v187, 2, v164
	v_mul_lo_u32 v189, v132, s82
	v_lshlrev_b32_e32 v191, 4, v185
	v_mul_u32_u24_e32 v192, 0x90, v184
	v_and_b32_e32 v193, 32, v164
	s_cmp_eq_u32 s30, 0x100
	s_cselect_b32 s40, 8, s30
	s_lshl_b32 s40, s40, 18
	s_mov_b32 s41, 0
	v_add_u32_e32 v194, 0xfffff400, v5
	v_add_u32_e32 v195, 0xffffff40, v164
	v_add_u32_e32 v196, 64, v135
	v_lshl_add_u64 v[148:149], v[10:11], 0, s[38:39]
	v_add_u32_e32 v197, v3, v142
	v_add_u32_e32 v198, v7, v134
	v_add_u32_e32 v199, v1, v9
	v_add_u32_e32 v200, v14, v15
	v_lshlrev_b32_e32 v150, 1, v2
	v_add_u32_e32 v201, v14, v16
	v_lshlrev_b32_e32 v152, 1, v4
	v_add_u32_e32 v202, v14, v17
	v_lshlrev_b32_e32 v154, 1, v6
	v_add_u32_e32 v203, v14, v18
	v_lshlrev_b32_e32 v156, 1, v8
	s_mov_b32 s31, s46
	s_branch .LBB0_43
.LBB0_42:
	v_lshl_add_u64 v[146:147], v[146:147], 0, s[40:41]
	s_cmp_eq_u32 s30, 0x100
	s_cbranch_scc0 .Latt_bh_old
	s_add_i32 s46, s46, 8
	s_add_i32 s31, s31, 8
	s_and_b32 s38, s46, 0x18
	s_cmp_eq_u32 s38, 0
	s_cbranch_scc1 .LBB0_75
	s_branch .LBB0_43
.Latt_bh_old:
	s_add_i32 s46, s46, s30
	s_add_i32 s31, s31, s30
	s_cmpk_gt_i32 s46, 0xff
	s_cbranch_scc1 .LBB0_75
.LBB0_43:
	s_ashr_i32 s47, s46, 31
	s_ashr_i32 s54, s46, 4
	s_lshl_b64 s[38:39], s[46:47], 11
	s_and_b32 s50, s46, 15
	v_lshl_add_u64 v[2:3], s[38:39], 0, v[132:133]
	s_lshl_b32 s48, s54, 5
	v_lshlrev_b64 v[2:3], 7, v[2:3]
	s_ashr_i32 s49, s48, 31
	s_lshl_b32 s58, s50, 6
	s_lshl_b32 s55, s54, 11
	v_lshl_add_u64 v[158:159], v[136:137], 0, v[2:3]
	v_lshl_add_u64 v[2:3], s[58:59], 0, v[132:133]
	s_lshl_b64 s[48:49], s[48:49], 17
	v_lshlrev_b64 v[2:3], 7, v[2:3]
	v_lshl_add_u64 v[4:5], v[138:139], 0, s[48:49]
	v_or_b32_e32 v1, s55, v164
	s_and_b32 s52, s31, 15
	v_lshl_add_u64 v[160:161], v[4:5], 0, v[2:3]
	v_add_u32_e32 v2, 0xffffff00, v1
	s_lshl_b32 s53, s52, 13
	s_add_i32 s35, s55, s27
	s_lshl_b32 s58, s50, 7
	v_lshl_or_b32 v4, v2, 4, s50
	v_ashrrev_i32_e32 v3, 31, v2
	s_mulk_i32 s50, 0xc0
	v_lshl_add_u64 v[168:169], v[2:3], 2, s[22:23]
	v_add_u32_e32 v2, s55, v135
	s_add_u32 s50, s7, s50
	v_ashrrev_i32_e32 v3, 31, v2
	s_addc_u32 s51, s25, 0
	s_lshl_b32 s39, s54, 15
	v_ashrrev_i32_e32 v5, 31, v4
	v_lshlrev_b64 v[2:3], 6, v[2:3]
	s_or_b32 s39, s52, s39
	s_or_b32 s48, s48, s53
	s_mov_b32 s38, 7
	v_lshl_add_u64 v[162:163], v[140:141], 0, s[58:59]
	v_lshl_add_u64 v[166:167], v[4:5], 2, s[8:9]
	v_lshl_add_u64 v[170:171], v[144:145], 0, v[2:3]
	v_add_u32_e32 v204, s39, v194
	v_add_u32_e32 v205, s55, v195
	v_add_u32_e32 v228, s55, v196
	v_lshl_add_u64 v[172:173], v[148:149], 0, s[48:49]
	s_mov_b32 s38, 7
	s_mov_b32 s39, 7
	s_cmp_eq_u32 s30, 0x100
	s_cbranch_scc0 .Latt_qb_set
	s_lshr_b32 s38, s34, 3
	s_and_b32 s38, s38, 3
	s_mov_b32 s39, 1
.Latt_qb_set:
	s_lshl_b32 s47, s38, 2
	s_add_i32 s47, s47, 3
	s_branch .LBB0_45
.LBB0_44:
	v_mov_b32_e32 v1, v151
	s_nop 1
	v_permlane32_swap_b32_e32 v151, v1
	v_add_f32_e32 v1, v151, v1
	v_rcp_f32_e32 v2, v1
	v_add_u32_e32 v1, 0xc000, v199
	s_waitcnt lgkmcnt(0)
	s_barrier
	s_nop 1
	v_pk_mul_f32 v[4:5], v[2:3], v[32:33] op_sel_hi:[0,1]
	v_pk_mul_f32 v[6:7], v[2:3], v[34:35] op_sel_hi:[0,1]
	v_cvt_pk_bf16_f32 v4, v4, v5
	v_cvt_pk_bf16_f32 v5, v6, v7
	v_pk_mul_f32 v[6:7], v[2:3], v[16:17] op_sel_hi:[0,1]
	v_pk_mul_f32 v[8:9], v[2:3], v[18:19] op_sel_hi:[0,1]
	v_cvt_pk_bf16_f32 v6, v6, v7
	v_cvt_pk_bf16_f32 v7, v8, v9
	v_pk_mul_f32 v[8:9], v[2:3], v[36:37] op_sel_hi:[0,1]
	v_pk_mul_f32 v[10:11], v[2:3], v[38:39] op_sel_hi:[0,1]
	v_cvt_pk_bf16_f32 v8, v8, v9
	v_cvt_pk_bf16_f32 v9, v10, v11
	v_pk_mul_f32 v[10:11], v[2:3], v[20:21] op_sel_hi:[0,1]
	v_pk_mul_f32 v[12:13], v[2:3], v[22:23] op_sel_hi:[0,1]
	v_cvt_pk_bf16_f32 v10, v10, v11
	v_cvt_pk_bf16_f32 v11, v12, v13
	ds_write2_b64 v1, v[4:5], v[8:9] offset1:2
	ds_write2_b64 v1, v[6:7], v[10:11] offset0:8 offset1:10
	v_pk_mul_f32 v[4:5], v[2:3], v[40:41] op_sel_hi:[0,1]
	v_pk_mul_f32 v[6:7], v[2:3], v[42:43] op_sel_hi:[0,1]
	v_cvt_pk_bf16_f32 v4, v4, v5
	v_cvt_pk_bf16_f32 v5, v6, v7
	v_pk_mul_f32 v[6:7], v[2:3], v[24:25] op_sel_hi:[0,1]
	v_pk_mul_f32 v[8:9], v[2:3], v[26:27] op_sel_hi:[0,1]
	v_cvt_pk_bf16_f32 v6, v6, v7
	v_cvt_pk_bf16_f32 v7, v8, v9
	v_pk_mul_f32 v[8:9], v[2:3], v[44:45] op_sel_hi:[0,1]
	v_pk_mul_f32 v[10:11], v[2:3], v[46:47] op_sel_hi:[0,1]
	v_cvt_pk_bf16_f32 v8, v8, v9
	v_cvt_pk_bf16_f32 v9, v10, v11
	v_pk_mul_f32 v[10:11], v[2:3], v[28:29] op_sel_hi:[0,1]
	v_pk_mul_f32 v[2:3], v[2:3], v[30:31] op_sel_hi:[0,1]
	v_cvt_pk_bf16_f32 v10, v10, v11
	v_cvt_pk_bf16_f32 v11, v2, v3
	ds_write2_b64 v1, v[4:5], v[8:9] offset0:4 offset1:6
	ds_write2_b64 v1, v[6:7], v[10:11] offset0:12 offset1:14
	s_waitcnt lgkmcnt(0)
	ds_read_b128 v[2:5], v200 offset:49152
	ds_read_b128 v[6:9], v201 offset:49152
	s_ashr_i32 s53, s52, 31
	s_lshl_b64 s[48:49], s[52:53], 11
	v_lshl_add_u64 v[10:11], v[162:163], 0, s[48:49]
	v_mov_b32_e32 v151, v0
	v_lshl_add_u64 v[12:13], v[10:11], 0, v[150:151]
	v_mov_b32_e32 v153, v0
	s_waitcnt lgkmcnt(1)
	global_store_dwordx4 v[12:13], v[2:5], off
	v_lshl_add_u64 v[12:13], v[10:11], 0, v[152:153]
	ds_read_b128 v[2:5], v202 offset:49152
	s_waitcnt lgkmcnt(1)
	global_store_dwordx4 v[12:13], v[6:9], off
	ds_read_b128 v[6:9], v203 offset:49152
	v_mov_b32_e32 v155, v0
	v_lshl_add_u64 v[12:13], v[10:11], 0, v[154:155]
	v_mov_b32_e32 v157, v0
	s_waitcnt lgkmcnt(1)
	global_store_dwordx4 v[12:13], v[2:5], off
	s_nop 0
	s_nop 0
	v_lshl_add_u64 v[2:3], v[10:11], 0, v[156:157]
	s_waitcnt lgkmcnt(0)
	global_store_dwordx4 v[2:3], v[6:9], off
	s_waitcnt lgkmcnt(0)
	s_cmp_eq_u32 s39, 0
	s_cbranch_scc1 .LBB0_42
	s_add_i32 s39, s39, -1
	s_add_i32 s38, s38, -1
	s_cmp_eq_u32 s30, 0x100
	s_cbranch_scc0 .Latt_qb_next
	s_sub_i32 s38, 6, s38
.Latt_qb_next:
	s_lshl_b32 s47, s38, 2
	s_add_i32 s47, s47, 3

.Latt2_exit:
	v_lshlrev_b32_e32 v1, 4, v164
	v_add_u32_e32 v1, 0x14000, v1
	ds_read_b128 v[194:197], v1
	ds_read_b128 v[198:201], v1 offset:8192
	ds_read_b128 v[202:205], v1 offset:16384
	s_waitcnt lgkmcnt(0)
	s_branch .LBB0_44
	s_nop 0
	s_nop 0
	s_nop 0
	s_nop 0
	s_nop 0
	s_nop 0
	s_nop 0
	s_nop 0
	s_nop 0
	s_nop 0
	s_nop 0
	s_nop 0
	s_nop 0
.LBB0_75:
	v_readlane_b32 s54, v255, 12
	s_mov_b64 s[8:9], 0
	v_readlane_b32 s55, v255, 13
	v_readlane_b32 s27, v255, 31
